# MLA attention steady loop: QK-chain K-fragment LDS reads issued ahead into unused VGPRs with counted lgkmcnt waits
# speedup vs baseline: 1.0140x; 1.0058x over previous
.LBB0_223:
	s_add_i32 s3, s13, 32
	v_add3_u32 v153, s3, v133, v132
	v_add3_u32 v152, s3, v134, v132
	ds_read_b128 v[216:219], v153
	ds_read_b128 v[240:243], v152
	ds_read_b128 v[244:247], v153 offset:4096
	ds_read_b128 v[248:251], v152 offset:4096
	s_add_i32 s70, s19, 2
	s_mul_i32 s8, s70, 0x3000
	s_mul_hi_u32 s3, s70, 0x3000
	s_add_u32 s42, s5, s8
	s_addc_u32 s43, s11, s3
	s_cmp_lg_u32 32, -1
	s_cselect_b32 s3, 32, 0
	s_add_i32 s3, s17, s3
	v_add_u32_e32 v66, s3, v129
	v_add_u32_e32 v67, s3, v130
	v_readfirstlane_b32 s8, v66
	s_lshl_b64 s[44:45], s[70:71], 7
	v_lshl_add_u64 v[64:65], v[192:193], 1, s[42:43]
	s_mov_b32 m0, s8
	v_readfirstlane_b32 s3, v67
	v_add_u32_e32 v68, 0x2000, v66
	s_add_u32 s44, s12, s44
	global_load_lds_dwordx4 v[64:65], off
	v_lshl_add_u64 v[64:65], v[120:121], 1, s[42:43]
	s_mov_b32 m0, s3
	v_readfirstlane_b32 s3, v68
	v_add_u32_e32 v66, 0x3000, v66
	s_addc_u32 s45, s16, s45
	global_load_lds_dwordx4 v[64:65], off
	v_lshl_add_u64 v[64:65], v[122:123], 1, s[42:43]
	s_mov_b32 m0, s3
	v_readfirstlane_b32 s3, v66
	v_add_u32_e32 v66, 0x3000, v67
	global_load_lds_dwordx4 v[64:65], off
	v_lshl_add_u64 v[64:65], v[124:125], 1, s[44:45]
	s_mov_b32 m0, s3
	v_readfirstlane_b32 s3, v66
	global_load_lds_dwordx4 v[64:65], off
	v_lshl_add_u64 v[64:65], v[126:127], 1, s[44:45]
	s_mov_b32 m0, s3
	s_mov_b32 s18, s13
	global_load_lds_dwordx4 v[64:65], off
	s_add_i32 s8, s18, 32
	v_add_u32_e32 v64, s8, v131
	s_mov_b32 s13, s2
	s_mov_b64 s[2:3], -1
	s_andn2_b64 vcc, exec, s[28:29]
	v_add3_u32 v151, s8, v135, v132
	v_add3_u32 v150, s8, v138, v132
	v_add_u32_e32 v143, v64, v140
	v_add_u32_e32 v142, v64, v141
	s_cbranch_vccz .LBB0_225
	s_mov_b64 s[2:3], 0
	ds_read_b128 v[154:157], v151
	s_waitcnt lgkmcnt(4)
	v_mfma_f32_32x32x16_bf16 v[80:95], v[216:219], v[116:119], 0
	ds_read_b128 v[216:219], v151 offset:4096
	s_waitcnt lgkmcnt(4)
	v_mfma_f32_32x32x16_bf16 v[80:95], v[240:243], v[112:115], v[80:95]
	ds_read_b128 v[240:243], v150
	s_waitcnt lgkmcnt(4)
	v_mfma_f32_32x32x16_bf16 v[64:79], v[244:247], v[116:119], 0
	ds_read_b128 v[244:247], v150 offset:4096
	s_waitcnt lgkmcnt(4)
	v_mfma_f32_32x32x16_bf16 v[64:79], v[248:251], v[112:115], v[64:79]
	ds_read_b128 v[248:251], v143 offset:8192
	s_waitcnt lgkmcnt(4)
	v_mfma_f32_32x32x16_bf16 v[80:95], v[154:157], v[108:111], v[80:95]
	ds_read_b128 v[154:157], v143 offset:10240
	s_waitcnt lgkmcnt(4)
	v_mfma_f32_32x32x16_bf16 v[64:79], v[216:219], v[108:111], v[64:79]
	ds_read_b128 v[216:219], v142 offset:8192
	s_waitcnt lgkmcnt(4)
	v_mfma_f32_32x32x16_bf16 v[80:95], v[240:243], v[104:107], v[80:95]
	ds_read_b128 v[240:243], v142 offset:10240
	s_waitcnt lgkmcnt(4)
	v_mfma_f32_32x32x16_bf16 v[64:79], v[244:247], v[104:107], v[64:79]
	s_waitcnt lgkmcnt(3)
	v_mfma_f32_32x32x16_bf16 v[80:95], v[248:251], v[100:103], v[80:95]
	s_waitcnt lgkmcnt(2)
	v_mfma_f32_32x32x16_bf16 v[64:79], v[154:157], v[100:103], v[64:79]
	s_waitcnt lgkmcnt(1)
	v_mfma_f32_32x32x16_bf16 v[80:95], v[216:219], v[96:99], v[80:95]
	s_waitcnt lgkmcnt(0)
	v_mfma_f32_32x32x16_bf16 v[64:79], v[240:243], v[96:99], v[64:79]

.LBB0_230:
	s_add_i32 s48, s13, 32
	v_add_u32_e32 v142, s48, v139
	v_exp_f32_e32 v150, v32
	v_add_u32_e32 v32, v142, v148
	v_exp_f32_e32 v143, v48
	v_exp_f32_e32 v151, v49
	v_exp_f32_e32 v153, v50
	v_exp_f32_e32 v154, v51
	ds_read_b128 v[48:51], v32 offset:12288
	v_exp_f32_e32 v155, v52
	v_exp_f32_e32 v156, v53
	v_exp_f32_e32 v159, v54
	v_exp_f32_e32 v158, v55
	ds_read_b128 v[166:169], v32 offset:16384
	v_cvt_pk_bf16_f32 v52, v143, v151
	v_cvt_pk_bf16_f32 v53, v153, v154
	v_cvt_pk_bf16_f32 v54, v155, v156
	v_cvt_pk_bf16_f32 v55, v159, v158
	v_add_u32_e32 v32, v142, v147
	v_exp_f32_e32 v157, v56
	s_waitcnt lgkmcnt(0)
	v_mfma_f32_32x32x16_bf16 v[16:31], v[48:51], v[52:55], v[16:31]
	ds_read_b128 v[48:51], v32 offset:12288
	v_exp_f32_e32 v165, v57
	v_exp_f32_e32 v163, v58
	v_exp_f32_e32 v162, v59
	v_exp_f32_e32 v161, v60
	v_exp_f32_e32 v160, v61
	v_exp_f32_e32 v164, v63
	v_mfma_f32_32x32x16_bf16 v[0:15], v[166:169], v[52:55], v[0:15]
	v_exp_f32_e32 v166, v62
	v_cvt_pk_bf16_f32 v52, v157, v165
	v_cvt_pk_bf16_f32 v53, v163, v162
	v_cvt_pk_bf16_f32 v54, v161, v160
	v_cvt_pk_bf16_f32 v55, v166, v164
	v_exp_f32_e32 v152, v33
	ds_read_b128 v[56:59], v32 offset:16384
	s_waitcnt lgkmcnt(0)
	v_mfma_f32_32x32x16_bf16 v[16:31], v[48:51], v[52:55], v[16:31]
	v_add_u32_e32 v48, v142, v146
	v_exp_f32_e32 v172, v34
	v_exp_f32_e32 v170, v35
	ds_read_b128 v[32:35], v48 offset:12288
	v_exp_f32_e32 v169, v36
	v_exp_f32_e32 v168, v37
	v_exp_f32_e32 v167, v38
	v_exp_f32_e32 v173, v39
	v_exp_f32_e32 v171, v40
	v_cvt_pk_bf16_f32 v36, v150, v152
	v_cvt_pk_bf16_f32 v37, v172, v170
	v_cvt_pk_bf16_f32 v38, v169, v168
	v_cvt_pk_bf16_f32 v39, v167, v173
	ds_read_b128 v[48:51], v48 offset:16384
	v_add_u32_e32 v40, v142, v145
	v_mfma_f32_32x32x16_bf16 v[0:15], v[56:59], v[52:55], v[0:15]
	s_add_i32 s2, s19, 3
	s_mul_i32 s44, s2, 0x3000
	s_mul_hi_u32 s19, s2, 0x3000
	s_add_u32 s46, s5, s44
	v_exp_f32_e32 v179, v41
	v_exp_f32_e32 v177, v42
	v_exp_f32_e32 v176, v43
	s_waitcnt lgkmcnt(0)
	v_mfma_f32_32x32x16_bf16 v[16:31], v[32:35], v[36:39], v[16:31]
	ds_read_b128 v[32:35], v40 offset:12288
	v_exp_f32_e32 v175, v44
	v_exp_f32_e32 v174, v45
	v_exp_f32_e32 v180, v46
	v_exp_f32_e32 v178, v47
	s_addc_u32 s47, s11, s19
	s_cmp_lg_u32 32, -1
	s_cselect_b32 s19, 32, 0
	s_mov_b32 s3, s71
	s_add_i32 s19, s13, s19
	v_mfma_f32_32x32x16_bf16 v[0:15], v[48:51], v[36:39], v[0:15]
	v_cvt_pk_bf16_f32 v36, v171, v179
	v_cvt_pk_bf16_f32 v37, v177, v176
	v_cvt_pk_bf16_f32 v38, v175, v174
	v_cvt_pk_bf16_f32 v39, v180, v178
	s_lshl_b64 s[2:3], s[2:3], 7
	s_add_u32 s44, s12, s2
	ds_read_b128 v[40:43], v40 offset:16384
	s_waitcnt lgkmcnt(0)
	v_mfma_f32_32x32x16_bf16 v[16:31], v[32:35], v[36:39], v[16:31]
	v_add_u32_e32 v34, s19, v129
	v_add_u32_e32 v35, s19, v130
	v_readfirstlane_b32 s2, v34
	v_lshl_add_u64 v[32:33], v[192:193], 1, s[46:47]
	s_mov_b32 m0, s2
	v_readfirstlane_b32 s2, v35
	v_add_u32_e32 v44, 0x2000, v34
	s_waitcnt vmcnt(0)
	s_waitcnt vmcnt(0)
	s_barrier
	s_add_i32 vcc_lo, s17, 32
	v_add3_u32 v186, vcc_lo, v133, v132
	v_add3_u32 v185, vcc_lo, v134, v132
	ds_read_b128 v[216:219], v186
	ds_read_b128 v[240:243], v185
	ds_read_b128 v[244:247], v186 offset:4096
	ds_read_b128 v[248:251], v185 offset:4096
	global_load_lds_dwordx4 v[32:33], off
	v_lshl_add_u64 v[32:33], v[120:121], 1, s[46:47]
	s_mov_b32 m0, s2
	v_readfirstlane_b32 s2, v44
	v_add_u32_e32 v34, 0x3000, v34
	s_addc_u32 s45, s16, s3
	global_load_lds_dwordx4 v[32:33], off
	v_lshl_add_u64 v[32:33], v[122:123], 1, s[46:47]
	s_mov_b32 m0, s2
	v_readfirstlane_b32 s2, v34
	v_add_u32_e32 v34, 0x3000, v35
	global_load_lds_dwordx4 v[32:33], off
	v_lshl_add_u64 v[32:33], v[124:125], 1, s[44:45]
	s_mov_b32 m0, s2
	v_readfirstlane_b32 s2, v34
	global_load_lds_dwordx4 v[32:33], off
	v_lshl_add_u64 v[32:33], v[126:127], 1, s[44:45]
	s_mov_b32 m0, s2
	v_mfma_f32_32x32x16_bf16 v[0:15], v[40:43], v[36:39], v[0:15]
	global_load_lds_dwordx4 v[32:33], off
	s_add_i32 s19, s17, 32
	v_add_u32_e32 v32, s19, v131
	s_mov_b64 s[2:3], -1
	s_andn2_b64 vcc, exec, s[28:29]
	v_add3_u32 v184, s19, v135, v132
	v_add3_u32 v183, s19, v138, v132
	v_add_u32_e32 v182, v32, v140
	v_add_u32_e32 v181, v32, v141
	s_cbranch_vccz .LBB0_232
	s_mov_b64 s[2:3], 0
	ds_read_b128 v[188:191], v184
	s_waitcnt lgkmcnt(4)
	v_mfma_f32_32x32x16_bf16 v[48:63], v[216:219], v[116:119], 0
	ds_read_b128 v[216:219], v184 offset:4096
	s_waitcnt lgkmcnt(4)
	v_mfma_f32_32x32x16_bf16 v[48:63], v[240:243], v[112:115], v[48:63]
	ds_read_b128 v[240:243], v183
	s_waitcnt lgkmcnt(4)
	v_mfma_f32_32x32x16_bf16 v[32:47], v[244:247], v[116:119], 0
	ds_read_b128 v[244:247], v183 offset:4096
	s_waitcnt lgkmcnt(4)
	v_mfma_f32_32x32x16_bf16 v[32:47], v[248:251], v[112:115], v[32:47]
	ds_read_b128 v[248:251], v182 offset:8192
	s_waitcnt lgkmcnt(4)
	v_mfma_f32_32x32x16_bf16 v[48:63], v[188:191], v[108:111], v[48:63]
	ds_read_b128 v[188:191], v182 offset:10240
	s_waitcnt lgkmcnt(4)
	v_mfma_f32_32x32x16_bf16 v[32:47], v[216:219], v[108:111], v[32:47]
	ds_read_b128 v[216:219], v181 offset:8192
	s_waitcnt lgkmcnt(4)
	v_mfma_f32_32x32x16_bf16 v[48:63], v[240:243], v[104:107], v[48:63]
	ds_read_b128 v[240:243], v181 offset:10240
	s_waitcnt lgkmcnt(4)
	v_mfma_f32_32x32x16_bf16 v[32:47], v[244:247], v[104:107], v[32:47]
	s_waitcnt lgkmcnt(3)
	v_mfma_f32_32x32x16_bf16 v[48:63], v[248:251], v[100:103], v[48:63]
	s_waitcnt lgkmcnt(2)
	v_mfma_f32_32x32x16_bf16 v[32:47], v[188:191], v[100:103], v[32:47]
	s_waitcnt lgkmcnt(1)
	v_mfma_f32_32x32x16_bf16 v[48:63], v[216:219], v[96:99], v[48:63]
	s_waitcnt lgkmcnt(0)
	v_mfma_f32_32x32x16_bf16 v[32:47], v[240:243], v[96:99], v[32:47]
